# v13 + attention: interior key tiles use the tile-uniform mask only (the two per-element window compares are always true there)
# baseline (speedup 1.0000x reference)
; __device__ __forceinline__ void attn_unit(const AtArgs& A, unsigned char* lds, int unit, int tid, int wave, int lane) {
;     ...
;         const bf16x8 qa0 = *(const bf16x8*)(QS + fr * QST + fq * 8), qa1 = *(const bf16x8*)(QS + fr * QST + 32 + fq * 8);
;         f32x4 sc[9];
; #pragma unroll
;         for (int kt = 0; kt < 9; ++kt) {
;             const int key = (q0 / 16 + kt) * 16 + fr;
;             const bf16x8 kb0 = *(const bf16x8*)(KS + key * KST + fq * 8), kb1 = *(const bf16x8*)(KS + key * KST + 32 + fq * 8);
;             f32x4 a = (f32x4){0.f, 0.f, 0.f, 0.f};
;             a = __builtin_amdgcn_mfma_f32_16x16x32_bf16(qa0, kb0, a, 0, 0, 0); a = __builtin_amdgcn_mfma_f32_16x16x32_bf16(qa1, kb1, a, 0, 0, 0);
; #pragma unroll
;             for (int r = 0; r < 4; ++r) {
;                 const int qi = q0 + fq * 4 + r;
;                 const bool ok = (key > qi) && (key <= qi + 128) && (nb > 0 || key >= 128);
;                 a[r] = ok ? a[r] : -1e30f;
;             }
;             sc[kt] = a;
;         }
.LBB0_510:
	s_or_b64 exec, exec, s[0:1]
	v_pk_mul_f32 v[18:19], v[60:61], s[14:15] op_sel_hi:[1,0]
	v_pk_mul_f32 v[20:21], v[28:29], s[14:15] op_sel_hi:[1,0]
	v_pk_mul_f32 v[22:23], v[24:25], s[14:15] op_sel_hi:[1,0]
	v_pk_mul_f32 v[12:13], v[12:13], s[14:15] op_sel_hi:[1,0]
	v_pk_mul_f32 v[24:25], v[8:9], s[14:15] op_sel_hi:[1,0]
	v_pk_mul_f32 v[26:27], v[10:11], s[14:15] op_sel_hi:[1,0]
	v_pk_mul_f32 v[14:15], v[14:15], s[14:15] op_sel_hi:[1,0]
	v_pk_mul_f32 v[16:17], v[16:17], s[14:15] op_sel_hi:[1,0]
	v_cvt_pk_bf16_f32 v8, v18, v19
	v_cvt_pk_bf16_f32 v9, v20, v21
	v_cvt_pk_bf16_f32 v10, v22, v23
	v_cvt_pk_bf16_f32 v11, v12, v13
	v_cvt_pk_bf16_f32 v12, v24, v25
	v_cvt_pk_bf16_f32 v13, v26, v27
	v_cvt_pk_bf16_f32 v14, v14, v15
	v_cvt_pk_bf16_f32 v15, v16, v17
	ds_write_b128 v75, v[8:11]
	ds_write_b128 v75, v[12:15] offset:16
	s_waitcnt lgkmcnt(0)
	ds_read_b128 v[12:15], v76
	ds_read_b128 v[8:11], v76 offset:64
	ds_read_b128 v[16:19], v95
	ds_read_b128 v[20:23], v95 offset:64
	s_waitcnt lgkmcnt(1)
	v_mfma_f32_16x16x32_bf16 v[16:19], v[12:15], v[16:19], 0
	v_add_u32_e32 v30, s2, v85
	v_add_u32_e32 v31, s2, v88
	v_add_u32_e32 v58, 1, v31
	s_waitcnt lgkmcnt(0)
	v_mfma_f32_16x16x32_bf16 v[16:19], v[8:11], v[20:23], v[16:19]
	v_add_u32_e32 v20, 0xffffff80, v30
	v_cmp_ge_i32_e32 vcc, v31, v20
	s_and_b64 s[0:1], s[42:43], vcc
	s_and_b64 vcc, s[16:17], s[0:1]
	v_cmp_ge_i32_e64 s[0:1], v58, v20
	s_nop 2
	v_cndmask_b32_e32 v29, v93, v16, vcc
	v_cmp_gt_i32_e32 vcc, v30, v58
	s_and_b64 s[0:1], vcc, s[0:1]
	s_and_b64 vcc, s[16:17], s[0:1]
	v_add_u32_e32 v59, 2, v31
	ds_read_b128 v[96:99], v95 offset:2304
	ds_read_b128 v[100:103], v95 offset:2368
	v_cndmask_b32_e32 v22, v93, v17, vcc
	v_cmp_gt_i32_e32 vcc, v30, v59
	v_cmp_ge_i32_e64 s[0:1], v59, v20
	s_and_b64 s[0:1], vcc, s[0:1]
	s_and_b64 vcc, s[16:17], s[0:1]
	v_add_u32_e32 v60, 3, v31
	v_cndmask_b32_e32 v18, v93, v18, vcc
	v_cmp_gt_i32_e32 vcc, v30, v60
	v_cmp_ge_i32_e64 s[0:1], v60, v20
	s_waitcnt lgkmcnt(1)
	v_mfma_f32_16x16x32_bf16 v[96:99], v[12:15], v[96:99], 0
	s_and_b64 s[0:1], vcc, s[0:1]
	s_add_i32 s6, s4, s2
	s_and_b64 vcc, s[16:17], s[0:1]
	s_add_i32 s0, s6, 16
	s_cmpk_gt_u32 s0, 0x7f
	v_cndmask_b32_e32 v16, v93, v19, vcc
	v_add_u32_e32 v17, 16, v30
	s_waitcnt lgkmcnt(0)
	v_mfma_f32_16x16x32_bf16 v[96:99], v[8:11], v[100:103], v[96:99]
	v_add_u32_e32 v19, 0xffffff90, v30
	s_cselect_b64 s[0:1], -1, 0
	s_or_b64 s[10:11], s[16:17], s[0:1]
	s_nop 0
	s_nop 0
	s_nop 0
	s_mov_b64 vcc, s[10:11]
	s_nop 0
	v_cndmask_b32_e32 v96, v93, v96, vcc
	s_nop 0
	s_nop 0
	s_nop 0
	s_mov_b64 vcc, s[10:11]
	v_cndmask_b32_e32 v26, v93, v97, vcc
	s_nop 0
	s_nop 0
	s_nop 0
	s_mov_b64 vcc, s[10:11]
	v_cndmask_b32_e32 v20, v93, v98, vcc
	s_nop 0
	s_nop 0
	s_nop 0
	s_mov_b64 vcc, s[10:11]
	v_cndmask_b32_e32 v17, v93, v99, vcc
	ds_read_b128 v[98:101], v95 offset:4608
	ds_read_b128 v[108:111], v95 offset:4672
	s_waitcnt lgkmcnt(1)
	v_mfma_f32_16x16x32_bf16 v[98:101], v[12:15], v[98:101], 0
	s_add_i32 s0, s6, 32
	s_cmpk_gt_u32 s0, 0x7f
	v_add_u32_e32 v19, 32, v30
	s_waitcnt lgkmcnt(0)
	v_mfma_f32_16x16x32_bf16 v[100:103], v[8:11], v[108:111], v[98:101]
	v_add_u32_e32 v21, 0xffffffa0, v30
	s_cselect_b64 s[0:1], -1, 0
	s_or_b64 s[10:11], s[16:17], s[0:1]
	s_nop 0
	s_nop 0
	s_nop 0
	s_mov_b64 vcc, s[10:11]
	s_nop 0
	v_cndmask_b32_e32 v100, v93, v100, vcc
	s_nop 0
	s_nop 0
	s_nop 0
	s_mov_b64 vcc, s[10:11]
	ds_read_b128 v[108:111], v95 offset:6912
	ds_read_b128 v[112:115], v95 offset:6976
	v_cndmask_b32_e32 v56, v93, v101, vcc
	s_nop 0
	s_nop 0
	s_nop 0
	s_mov_b64 vcc, s[10:11]
	v_cndmask_b32_e32 v23, v93, v102, vcc
	s_nop 0
	s_nop 0
	s_waitcnt lgkmcnt(1)
	v_mfma_f32_16x16x32_bf16 v[108:111], v[12:15], v[108:111], 0
	s_nop 0
	s_mov_b64 vcc, s[10:11]
	s_add_i32 s0, s6, 48
	s_cmpk_gt_u32 s0, 0x7f
	v_add_u32_e32 v21, 48, v30
	s_waitcnt lgkmcnt(0)
	v_mfma_f32_16x16x32_bf16 v[108:111], v[8:11], v[112:115], v[108:111]
	v_add_u32_e32 v25, 0xffffffb0, v30
	s_cselect_b64 s[0:1], -1, 0
	v_cndmask_b32_e32 v19, v93, v103, vcc
	s_or_b64 s[10:11], s[16:17], s[0:1]
	s_nop 0
	s_nop 0
	s_nop 0
	s_mov_b64 vcc, s[10:11]
	v_cndmask_b32_e32 v103, v93, v108, vcc
	s_nop 0
	s_nop 0
	s_nop 0
	s_mov_b64 vcc, s[10:11]
	v_cndmask_b32_e32 v97, v93, v109, vcc
	s_nop 0
	s_nop 0
	s_nop 0
	s_mov_b64 vcc, s[10:11]
	v_cndmask_b32_e32 v27, v93, v110, vcc
	s_nop 0
	s_nop 0
	s_nop 0
	s_mov_b64 vcc, s[10:11]
	v_cndmask_b32_e32 v21, v93, v111, vcc
	ds_read_b128 v[108:111], v95 offset:9216
	ds_read_b128 v[112:115], v95 offset:9280
	s_waitcnt lgkmcnt(1)
	v_mfma_f32_16x16x32_bf16 v[108:111], v[12:15], v[108:111], 0
	s_add_i32 s0, s6, 64
	s_cmpk_gt_u32 s0, 0x7f
	v_add_u32_e32 v25, 64, v30
	s_waitcnt lgkmcnt(0)
	v_mfma_f32_16x16x32_bf16 v[108:111], v[8:11], v[112:115], v[108:111]
	v_subrev_u32_e32 v28, 64, v30
	s_cselect_b64 s[0:1], -1, 0
	s_or_b64 s[10:11], s[16:17], s[0:1]
	s_nop 0
	s_nop 0
	s_nop 0
	s_mov_b64 vcc, s[10:11]
	s_nop 0
	v_cndmask_b32_e32 v116, v93, v108, vcc
	s_nop 0
	s_nop 0
	s_nop 0
	s_mov_b64 vcc, s[10:11]
	v_cndmask_b32_e32 v101, v93, v109, vcc
	s_nop 0
	s_nop 0
	s_nop 0
	s_mov_b64 vcc, s[10:11]
	v_cndmask_b32_e32 v57, v93, v110, vcc
	s_nop 0
	s_nop 0
	s_nop 0
	s_mov_b64 vcc, s[10:11]
	v_cndmask_b32_e32 v25, v93, v111, vcc
	ds_read_b128 v[108:111], v95 offset:11520
	ds_read_b128 v[112:115], v95 offset:11584
	s_waitcnt lgkmcnt(1)
	v_mfma_f32_16x16x32_bf16 v[108:111], v[12:15], v[108:111], 0
	s_add_i32 s0, s6, 0x50
	s_cmpk_gt_u32 s0, 0x7f
	v_add_u32_e32 v28, 0x50, v30
	s_waitcnt lgkmcnt(0)
; __device__ __forceinline__ float row16_sum(float v) { v += dpp_perm<0xB1, 0xF>(v); v += dpp_perm<0x4E, 0xF>(v); v += dpp_perm<0x141, 0xF>(v); v += dpp_perm<0x140, 0xF>(v); return v; }
; __device__ __forceinline__ float row16_max(float v) { v = fmaxf(v, dpp_perm<0xB1, 0xF>(v)); v = fmaxf(v, dpp_perm<0x4E, 0xF>(v)); v = fmaxf(v, dpp_perm<0x141, 0xF>(v)); v = fmaxf(v, dpp_perm<0x140, 0xF>(v)); return v; }
; __device__ __forceinline__ void attn_unit(const AtArgs& A, unsigned char* lds, int unit, int tid, int wave, int lane) {
;     ...
;         for (int kt = 0; kt < 9; ++kt) {
;             const int key = (q0 / 16 + kt) * 16 + fr;
;             const bf16x8 kb0 = *(const bf16x8*)(KS + key * KST + fq * 8), kb1 = *(const bf16x8*)(KS + key * KST + 32 + fq * 8);
;             f32x4 a = (f32x4){0.f, 0.f, 0.f, 0.f};
;             a = __builtin_amdgcn_mfma_f32_16x16x32_bf16(qa0, kb0, a, 0, 0, 0); a = __builtin_amdgcn_mfma_f32_16x16x32_bf16(qa1, kb1, a, 0, 0, 0);
; #pragma unroll
;             for (int r = 0; r < 4; ++r) {
;                 const int qi = q0 + fq * 4 + r;
;                 const bool ok = (key > qi) && (key <= qi + 128) && (nb > 0 || key >= 128);
;                 a[r] = ok ? a[r] : -1e30f;
;             }
;             sc[kt] = a;
;         }
;         float m4[4], s4[4];
; #pragma unroll
;         for (int r = 0; r < 4; ++r) {
;             float m = sc[0][r];
; #pragma unroll
;             for (int kt = 1; kt < 9; ++kt) m = fmaxf(m, sc[kt][r]);
;             m = row16_max(m);
;             m4[r] = fmaxf(m, sink);
;             float s = 0.f;
; #pragma unroll
;             for (int kt = 0; kt < 9; ++kt) { const float e = __expf(sc[kt][r] - m4[r]); sc[kt][r] = e; s += e; }
;             s = row16_sum(s);
;             s4[r] = __builtin_amdgcn_rcpf(s + __expf(sink - m4[r]));
	v_mfma_f32_16x16x32_bf16 v[108:111], v[8:11], v[112:115], v[108:111]
	v_subrev_u32_e32 v61, 48, v30
	s_cselect_b64 s[0:1], -1, 0
	s_or_b64 s[10:11], s[16:17], s[0:1]
	s_nop 0
	s_nop 0
	s_nop 0
	s_mov_b64 vcc, s[10:11]
	s_nop 0
	v_cndmask_b32_e32 v117, v93, v108, vcc
	s_nop 0
	s_nop 0
	s_nop 0
	s_mov_b64 vcc, s[10:11]
	v_cndmask_b32_e32 v118, v93, v109, vcc
	s_nop 0
	s_nop 0
	s_nop 0
	s_mov_b64 vcc, s[10:11]
	v_cndmask_b32_e32 v98, v93, v110, vcc
	s_nop 0
	s_nop 0
	s_nop 0
	s_mov_b64 vcc, s[10:11]
	v_cndmask_b32_e32 v28, v93, v111, vcc
	ds_read_b128 v[108:111], v95 offset:13824
	ds_read_b128 v[112:115], v95 offset:13888
	s_waitcnt lgkmcnt(1)
	v_mfma_f32_16x16x32_bf16 v[108:111], v[12:15], v[108:111], 0
	s_add_i32 s0, s6, 0x60
	s_cmpk_gt_u32 s0, 0x7f
	v_add_u32_e32 v61, 0x60, v30
	s_waitcnt lgkmcnt(0)
	v_mfma_f32_16x16x32_bf16 v[108:111], v[8:11], v[112:115], v[108:111]
	v_subrev_u32_e32 v99, 32, v30
	s_cselect_b64 s[0:1], -1, 0
	s_or_b64 s[10:11], s[16:17], s[0:1]
	s_nop 0
	s_nop 0
	s_nop 0
	s_mov_b64 vcc, s[10:11]
	s_nop 0
	v_cndmask_b32_e32 v119, v93, v108, vcc
	s_nop 0
	s_nop 0
	s_nop 0
	s_mov_b64 vcc, s[10:11]
	v_cndmask_b32_e32 v120, v93, v109, vcc
	s_nop 0
	s_nop 0
	s_nop 0
	s_mov_b64 vcc, s[10:11]
	v_cndmask_b32_e32 v102, v93, v110, vcc
	s_nop 0
	s_nop 0
	s_nop 0
	s_mov_b64 vcc, s[10:11]
	v_cndmask_b32_e32 v61, v93, v111, vcc
	ds_read_b128 v[108:111], v95 offset:16128
	ds_read_b128 v[112:115], v95 offset:16192
	s_waitcnt lgkmcnt(1)
	v_mfma_f32_16x16x32_bf16 v[108:111], v[12:15], v[108:111], 0
	s_addk_i32 s6, 0x70
	s_cmpk_gt_u32 s6, 0x7f
	v_add_u32_e32 v99, 0x70, v30
	s_waitcnt lgkmcnt(0)
	v_mfma_f32_16x16x32_bf16 v[108:111], v[8:11], v[112:115], v[108:111]
	v_add_u32_e32 v112, -16, v30
	s_cselect_b64 s[0:1], -1, 0
	s_or_b64 s[10:11], s[16:17], s[0:1]
	s_nop 0
	s_nop 0
	s_nop 0
	s_mov_b64 vcc, s[10:11]
	s_nop 0
	v_cndmask_b32_e32 v121, v93, v108, vcc
	s_nop 0
	s_nop 0
	s_nop 0
	s_mov_b64 vcc, s[10:11]
	v_cndmask_b32_e32 v122, v93, v109, vcc
	s_nop 0
	s_nop 0
	s_nop 0
	s_mov_b64 vcc, s[10:11]
	v_cndmask_b32_e32 v123, v93, v110, vcc
	s_nop 0
	s_nop 0
	s_nop 0
	s_mov_b64 vcc, s[10:11]
	v_cndmask_b32_e32 v99, v93, v111, vcc
	ds_read_b128 v[108:111], v95 offset:18432
	ds_read_b128 v[112:115], v95 offset:18496
	s_waitcnt lgkmcnt(1)
	v_mfma_f32_16x16x32_bf16 v[12:15], v[12:15], v[108:111], 0
	v_add_u32_e32 v124, 0x80, v30
	v_cmp_gt_i32_e32 vcc, v124, v31
	v_cmp_ge_i32_e64 s[0:1], v31, v30
	s_waitcnt lgkmcnt(0)
	v_mfma_f32_16x16x32_bf16 v[8:11], v[8:11], v[112:115], v[12:15]
	s_and_b64 vcc, vcc, s[0:1]
	v_cmp_ge_i32_e64 s[0:1], v58, v30
	v_add_u32_e32 v24, 0x900, v95
	v_mov_b32_e32 v95, 0
	v_mov_b32_e32 v108, 0
	s_nop 2
	v_cndmask_b32_e32 v8, v93, v8, vcc
	v_cmp_gt_i32_e32 vcc, v124, v58
	s_and_b64 vcc, vcc, s[0:1]
	v_cmp_ge_i32_e64 s[0:1], v59, v30
	v_cndmask_b32_e32 v58, v93, v9, vcc
	v_max3_f32 v9, v29, v96, v100
	v_cmp_gt_i32_e32 vcc, v124, v59
	v_max3_f32 v9, v9, v103, v116
	s_and_b64 vcc, vcc, s[0:1]
	v_max3_f32 v9, v9, v117, v119
	v_cndmask_b32_e32 v59, v93, v10, vcc
	v_max3_f32 v9, v9, v121, v8
	v_mov_b32_e32 v10, 0
	v_cmp_ge_i32_e64 s[0:1], v60, v30
	v_cmp_gt_i32_e32 vcc, v124, v60
	v_mov_b32_dpp v10, v9 quad_perm:[1,0,3,2] row_mask:0xf bank_mask:0xf
	v_max_f32_e32 v10, v10, v10
	v_max_f32_e32 v9, v9, v10
	v_mov_b32_e32 v10, 0
	s_and_b64 vcc, vcc, s[0:1]
	v_cndmask_b32_e32 v31, v93, v11, vcc
	v_mov_b32_dpp v10, v9 quad_perm:[2,3,0,1] row_mask:0xf bank_mask:0xf
	v_max_f32_e32 v10, v10, v10
	v_max_f32_e32 v9, v9, v10
	v_mov_b32_e32 v10, 0
	v_mov_b32_e32 v110, 0
	s_add_i32 s2, s2, 16
	v_mov_b32_dpp v10, v9 row_half_mirror row_mask:0xf bank_mask:0xf
	v_max_f32_e32 v10, v10, v10
	v_max_f32_e32 v9, v9, v10
	v_mov_b32_e32 v10, 0
	s_add_i32 s3, s3, 0xb000
	s_nop 0
	v_mov_b32_dpp v10, v9 row_mirror row_mask:0xf bank_mask:0xf
	v_max3_f32 v30, v9, v10, v38
	v_sub_f32_e32 v10, v96, v30
	v_mul_f32_e32 v10, 0x3fb8aa3b, v10
	v_sub_f32_e32 v9, v29, v30
	v_exp_f32_e32 v29, v10
	v_sub_f32_e32 v10, v100, v30
	v_mul_f32_e32 v9, 0x3fb8aa3b, v9
	v_mul_f32_e32 v10, 0x3fb8aa3b, v10
	v_exp_f32_e32 v14, v9
	v_exp_f32_e32 v15, v10
	v_sub_f32_e32 v10, v103, v30
	v_mul_f32_e32 v10, 0x3fb8aa3b, v10
	v_exp_f32_e32 v12, v10
	v_sub_f32_e32 v10, v116, v30
	v_sub_f32_e32 v11, v117, v30
	v_mul_f32_e32 v10, 0x3fb8aa3b, v10
	v_mul_f32_e32 v11, 0x3fb8aa3b, v11
	v_add_f32_e32 v9, 0, v14
	v_exp_f32_e32 v10, v10
	v_exp_f32_e32 v13, v11
	v_sub_f32_e32 v11, v119, v30
	v_add_f32_e32 v9, v29, v9
	v_mul_f32_e32 v11, 0x3fb8aa3b, v11
	v_add_f32_e32 v9, v15, v9
	v_exp_f32_e32 v11, v11
	v_add_f32_e32 v9, v12, v9
	v_add_f32_e32 v9, v10, v9
	v_add_f32_e32 v9, v13, v9
	v_add_f32_e32 v60, v11, v9
	v_sub_f32_e32 v9, v121, v30
	v_mul_f32_e32 v9, 0x3fb8aa3b, v9
	v_sub_f32_e32 v8, v8, v30
	v_exp_f32_e32 v9, v9
	v_mul_f32_e32 v8, 0x3fb8aa3b, v8
	v_exp_f32_e32 v8, v8
	v_sub_f32_e32 v30, v38, v30
	v_add_f32_e32 v60, v9, v60
	v_mul_f32_e32 v30, 0x3fb8aa3b, v30
	v_add_f32_e32 v60, v8, v60
	v_exp_f32_e32 v30, v30
	s_nop 0
	v_add_f32_dpp v60, v60, v60 quad_perm:[1,0,3,2] row_mask:0xf bank_mask:0xf bound_ctrl:1
	s_nop 1
	v_add_f32_dpp v60, v60, v60 quad_perm:[2,3,0,1] row_mask:0xf bank_mask:0xf bound_ctrl:1
	s_nop 1
	v_add_f32_dpp v60, v60, v60 row_half_mirror row_mask:0xf bank_mask:0xf bound_ctrl:1
	s_nop 1
	v_add_f32_dpp v60, v60, v60 row_mirror row_mask:0xf bank_mask:0xf bound_ctrl:1
	v_add_f32_e32 v30, v30, v60
	v_max3_f32 v60, v22, v26, v56
	v_max3_f32 v60, v60, v97, v101
	v_max3_f32 v60, v60, v118, v120
	v_max3_f32 v60, v60, v122, v58
	v_rcp_f32_e32 v30, v30
	s_nop 0
	v_mov_b32_dpp v95, v60 quad_perm:[1,0,3,2] row_mask:0xf bank_mask:0xf
	v_max_f32_e32 v95, v95, v95
	v_max_f32_e32 v60, v60, v95
; __device__ __forceinline__ unsigned f2bf(float f) { return pk2(f, f) & 0xffffu; }
; __device__ __forceinline__ float row16_sum(float v) { v += dpp_perm<0xB1, 0xF>(v); v += dpp_perm<0x4E, 0xF>(v); v += dpp_perm<0x141, 0xF>(v); v += dpp_perm<0x140, 0xF>(v); return v; }
; __device__ __forceinline__ float row16_max(float v) { v = fmaxf(v, dpp_perm<0xB1, 0xF>(v)); v = fmaxf(v, dpp_perm<0x4E, 0xF>(v)); v = fmaxf(v, dpp_perm<0x141, 0xF>(v)); v = fmaxf(v, dpp_perm<0x140, 0xF>(v)); return v; }
; __device__ __forceinline__ void attn_unit(const AtArgs& A, unsigned char* lds, int unit, int tid, int wave, int lane) {
;     ...
;         float m4[4], s4[4];
; #pragma unroll
;         for (int r = 0; r < 4; ++r) {
;             float m = sc[0][r];
; #pragma unroll
;             for (int kt = 1; kt < 9; ++kt) m = fmaxf(m, sc[kt][r]);
;             m = row16_max(m);
;             m4[r] = fmaxf(m, sink);
;             float s = 0.f;
; #pragma unroll
;             for (int kt = 0; kt < 9; ++kt) { const float e = __expf(sc[kt][r] - m4[r]); sc[kt][r] = e; s += e; }
;             s = row16_sum(s);
;             s4[r] = __builtin_amdgcn_rcpf(s + __expf(sink - m4[r]));
;         }
; #pragma unroll
;         for (int kt = 0; kt < 9; ++kt)
; #pragma unroll
;             for (int r = 0; r < 4; ++r) PS[(fq * 4 + r) * PST + kt * 16 + fr] = (bf16)f2bf(sc[kt][r] * s4[r]);
	v_mov_b32_e32 v95, 0
	v_mul_f32_e32 v14, v14, v30
	v_mul_f32_e32 v10, v10, v30
	v_mov_b32_dpp v95, v60 quad_perm:[2,3,0,1] row_mask:0xf bank_mask:0xf
	v_max_f32_e32 v95, v95, v95
	v_max_f32_e32 v60, v60, v95
	v_mov_b32_e32 v95, 0
	v_cvt_pk_bf16_f32 v14, v14, s0
	v_cvt_pk_bf16_f32 v10, v10, s0
	v_mov_b32_dpp v95, v60 row_half_mirror row_mask:0xf bank_mask:0xf
	v_max_f32_e32 v95, v95, v95
	v_max_f32_e32 v60, v60, v95
	v_mov_b32_e32 v95, 0
	ds_write_b16 v79, v14
	ds_write_b16 v79, v10 offset:128
	v_mov_b32_dpp v95, v60 row_mirror row_mask:0xf bank_mask:0xf
	v_max3_f32 v60, v60, v95, v38
	v_sub_f32_e32 v22, v22, v60
	v_mul_f32_e32 v22, 0x3fb8aa3b, v22
	v_sub_f32_e32 v26, v26, v60
	v_exp_f32_e32 v22, v22
	v_mul_f32_e32 v26, 0x3fb8aa3b, v26
	v_sub_f32_e32 v56, v56, v60
	v_exp_f32_e32 v26, v26
	v_mul_f32_e32 v56, 0x3fb8aa3b, v56
	v_sub_f32_e32 v96, v97, v60
	v_exp_f32_e32 v56, v56
	v_mul_f32_e32 v96, 0x3fb8aa3b, v96
	v_sub_f32_e32 v97, v101, v60
	v_exp_f32_e32 v96, v96
	v_mul_f32_e32 v97, 0x3fb8aa3b, v97
	v_sub_f32_e32 v100, v118, v60
	v_add_f32_e32 v95, 0, v22
	v_exp_f32_e32 v97, v97
	v_mul_f32_e32 v100, 0x3fb8aa3b, v100
	v_sub_f32_e32 v101, v120, v60
	v_add_f32_e32 v95, v26, v95
	v_exp_f32_e32 v100, v100
	v_mul_f32_e32 v101, 0x3fb8aa3b, v101
	v_sub_f32_e32 v103, v122, v60
	v_add_f32_e32 v95, v56, v95
	v_exp_f32_e32 v101, v101
	v_mul_f32_e32 v103, 0x3fb8aa3b, v103
	v_sub_f32_e32 v58, v58, v60
	v_add_f32_e32 v95, v96, v95
	v_exp_f32_e32 v103, v103
	v_mul_f32_e32 v58, 0x3fb8aa3b, v58
	v_add_f32_e32 v95, v97, v95
	v_exp_f32_e32 v58, v58
	v_add_f32_e32 v95, v100, v95
	v_add_f32_e32 v95, v101, v95
	v_add_f32_e32 v95, v103, v95
	v_sub_f32_e32 v60, v38, v60
	v_add_f32_e32 v95, v58, v95
	v_mul_f32_e32 v60, 0x3fb8aa3b, v60
	v_exp_f32_e32 v60, v60
	v_add_f32_dpp v95, v95, v95 quad_perm:[1,0,3,2] row_mask:0xf bank_mask:0xf bound_ctrl:1
	v_mul_f32_e32 v12, v12, v30
	v_mul_f32_e32 v9, v9, v30
	v_add_f32_dpp v95, v95, v95 quad_perm:[2,3,0,1] row_mask:0xf bank_mask:0xf bound_ctrl:1
	v_mul_f32_e32 v8, v8, v30
	v_cvt_pk_bf16_f32 v12, v12, s0
	v_add_f32_dpp v95, v95, v95 row_half_mirror row_mask:0xf bank_mask:0xf bound_ctrl:1
	v_cvt_pk_bf16_f32 v9, v9, s0
	v_cvt_pk_bf16_f32 v8, v8, s0
	v_add_f32_dpp v95, v95, v95 row_mirror row_mask:0xf bank_mask:0xf bound_ctrl:1
	v_add_f32_e32 v60, v60, v95
	v_max3_f32 v95, v18, v20, v23
	v_max3_f32 v95, v95, v27, v57
	v_max3_f32 v95, v95, v98, v102
	v_max3_f32 v95, v95, v123, v59
	v_rcp_f32_e32 v60, v60
	ds_write_b16 v79, v12 offset:96
	v_mov_b32_dpp v108, v95 quad_perm:[1,0,3,2] row_mask:0xf bank_mask:0xf
	v_max_f32_e32 v108, v108, v108
	v_max_f32_e32 v95, v95, v108
	v_mov_b32_e32 v108, 0
	v_mul_f32_e32 v14, v22, v60
	v_mul_f32_e32 v10, v97, v60
	v_mov_b32_dpp v108, v95 quad_perm:[2,3,0,1] row_mask:0xf bank_mask:0xf
	v_max_f32_e32 v108, v108, v108
	v_max_f32_e32 v95, v95, v108
	v_mov_b32_e32 v108, 0
	v_cvt_pk_bf16_f32 v14, v14, s0
	v_cvt_pk_bf16_f32 v10, v10, s0
	v_mov_b32_dpp v108, v95 row_half_mirror row_mask:0xf bank_mask:0xf
	v_max_f32_e32 v108, v108, v108
	v_max_f32_e32 v95, v95, v108
	v_mov_b32_e32 v108, 0
	ds_write_b16 v79, v14 offset:336
	ds_write_b16 v79, v10 offset:464
	v_mov_b32_dpp v108, v95 row_mirror row_mask:0xf bank_mask:0xf
	v_max3_f32 v95, v95, v108, v38
	v_sub_f32_e32 v18, v18, v95
	v_mul_f32_e32 v18, 0x3fb8aa3b, v18
	v_sub_f32_e32 v20, v20, v95
	v_exp_f32_e32 v18, v18
	v_mul_f32_e32 v20, 0x3fb8aa3b, v20
	v_sub_f32_e32 v23, v23, v95
	v_exp_f32_e32 v20, v20
	v_mul_f32_e32 v23, 0x3fb8aa3b, v23
	v_sub_f32_e32 v27, v27, v95
	v_exp_f32_e32 v23, v23
	v_mul_f32_e32 v27, 0x3fb8aa3b, v27
	v_sub_f32_e32 v57, v57, v95
	v_exp_f32_e32 v27, v27
	v_mul_f32_e32 v57, 0x3fb8aa3b, v57
	v_sub_f32_e32 v98, v98, v95
	v_add_f32_e32 v108, 0, v18
	v_exp_f32_e32 v57, v57
	v_mul_f32_e32 v98, 0x3fb8aa3b, v98
	v_sub_f32_e32 v102, v102, v95
	v_add_f32_e32 v108, v20, v108
	v_exp_f32_e32 v98, v98
	v_mul_f32_e32 v102, 0x3fb8aa3b, v102
	v_sub_f32_e32 v109, v123, v95
	v_add_f32_e32 v108, v23, v108
	v_exp_f32_e32 v102, v102
	v_mul_f32_e32 v109, 0x3fb8aa3b, v109
	v_sub_f32_e32 v59, v59, v95
	v_add_f32_e32 v108, v27, v108
	v_exp_f32_e32 v109, v109
	v_mul_f32_e32 v59, 0x3fb8aa3b, v59
	v_add_f32_e32 v108, v57, v108
	v_exp_f32_e32 v59, v59
	v_add_f32_e32 v108, v98, v108
	v_add_f32_e32 v108, v102, v108
	v_add_f32_e32 v108, v109, v108
	v_sub_f32_e32 v95, v38, v95
	v_add_f32_e32 v108, v59, v108
	v_mul_f32_e32 v95, 0x3fb8aa3b, v95
	v_exp_f32_e32 v95, v95
	v_add_f32_dpp v108, v108, v108 quad_perm:[1,0,3,2] row_mask:0xf bank_mask:0xf bound_ctrl:1
	v_mul_f32_e32 v12, v96, v60
	ds_write_b16 v79, v9 offset:224
	v_add_f32_dpp v108, v108, v108 quad_perm:[2,3,0,1] row_mask:0xf bank_mask:0xf bound_ctrl:1
	v_mul_f32_e32 v9, v103, v60
	ds_write_b16 v79, v8 offset:256
	v_add_f32_dpp v108, v108, v108 row_half_mirror row_mask:0xf bank_mask:0xf bound_ctrl:1
	v_mul_f32_e32 v8, v58, v60
	v_cvt_pk_bf16_f32 v12, v12, s0
	v_add_f32_dpp v108, v108, v108 row_mirror row_mask:0xf bank_mask:0xf bound_ctrl:1
	v_add_f32_e32 v95, v95, v108
	v_max3_f32 v108, v16, v17, v19
	v_max3_f32 v108, v108, v21, v25
	v_max3_f32 v108, v108, v28, v61
	v_max3_f32 v108, v108, v99, v31
	v_rcp_f32_e32 v95, v95
	v_cvt_pk_bf16_f32 v9, v9, s0
	v_mov_b32_dpp v110, v108 quad_perm:[1,0,3,2] row_mask:0xf bank_mask:0xf
	v_max_f32_e32 v110, v110, v110
	v_max_f32_e32 v108, v108, v110
	v_mov_b32_e32 v110, 0
	v_mul_f32_e32 v14, v18, v95
	v_mul_f32_e32 v10, v57, v95
	v_mov_b32_dpp v110, v108 quad_perm:[2,3,0,1] row_mask:0xf bank_mask:0xf
	v_max_f32_e32 v110, v110, v110
	v_max_f32_e32 v108, v108, v110
	v_mov_b32_e32 v110, 0
	v_cvt_pk_bf16_f32 v14, v14, s0
	v_cvt_pk_bf16_f32 v10, v10, s0
; __device__ __forceinline__ unsigned f2bf(float f) { return pk2(f, f) & 0xffffu; }
; #define LDS_WAIT() asm volatile("s_waitcnt lgkmcnt(0)" ::: "memory")
; __device__ __forceinline__ void attn_unit(const AtArgs& A, unsigned char* lds, int unit, int tid, int wave, int lane) {
;     ...
; #pragma unroll
;         for (int kt = 0; kt < 9; ++kt)
; #pragma unroll
;             for (int r = 0; r < 4; ++r) PS[(fq * 4 + r) * PST + kt * 16 + fr] = (bf16)f2bf(sc[kt][r] * s4[r]);
; #pragma unroll
;         for (int r = 0; r < 4; ++r) PS[(fq * 4 + r) * PST + 144 + fr] = 0;
;         LDS_WAIT();
;         f32x4 o[4];
; #pragma unroll
;         for (int dt = 0; dt < 4; ++dt) o[dt] = (f32x4){0.f, 0.f, 0.f, 0.f};
; #pragma unroll
;         for (int ks = 0; ks < 5; ++ks) {
;             const bf16x8 pa = *(const bf16x8*)(PS + fr * PST + ks * 32 + fq * 8);
; #pragma unroll
;             for (int dt = 0; dt < 4; ++dt) {
;                 const bf16x8 vb = *(const bf16x8*)(VT + (dt * 16 + fr) * VST + (((((q0 + ks * 32) >> 3) + fq) ^ ((dt * 2 + (fr >> 3)) & 7)) << 3));
	v_mov_b32_dpp v110, v108 row_half_mirror row_mask:0xf bank_mask:0xf
	v_max_f32_e32 v110, v110, v110
	v_max_f32_e32 v108, v108, v110
	v_mov_b32_e32 v110, 0
	ds_write_b16 v79, v14 offset:672
	ds_write_b16 v79, v10 offset:800
	v_mov_b32_dpp v110, v108 row_mirror row_mask:0xf bank_mask:0xf
	v_max3_f32 v108, v108, v110, v38
	v_sub_f32_e32 v16, v16, v108
	v_mul_f32_e32 v16, 0x3fb8aa3b, v16
	v_sub_f32_e32 v17, v17, v108
	v_exp_f32_e32 v16, v16
	v_mul_f32_e32 v17, 0x3fb8aa3b, v17
	v_sub_f32_e32 v19, v19, v108
	v_exp_f32_e32 v17, v17
	v_mul_f32_e32 v19, 0x3fb8aa3b, v19
	v_sub_f32_e32 v21, v21, v108
	v_exp_f32_e32 v19, v19
	v_mul_f32_e32 v21, 0x3fb8aa3b, v21
	v_sub_f32_e32 v25, v25, v108
	v_exp_f32_e32 v21, v21
	v_mul_f32_e32 v25, 0x3fb8aa3b, v25
	v_sub_f32_e32 v28, v28, v108
	v_add_f32_e32 v110, 0, v16
	v_exp_f32_e32 v25, v25
	v_mul_f32_e32 v28, 0x3fb8aa3b, v28
	v_sub_f32_e32 v61, v61, v108
	v_add_f32_e32 v110, v17, v110
	v_exp_f32_e32 v28, v28
	v_mul_f32_e32 v61, 0x3fb8aa3b, v61
	v_sub_f32_e32 v99, v99, v108
	v_add_f32_e32 v110, v19, v110
	v_exp_f32_e32 v61, v61
	v_mul_f32_e32 v99, 0x3fb8aa3b, v99
	v_sub_f32_e32 v31, v31, v108
	v_add_f32_e32 v110, v21, v110
	v_exp_f32_e32 v99, v99
	v_mul_f32_e32 v31, 0x3fb8aa3b, v31
	v_add_f32_e32 v110, v25, v110
	v_exp_f32_e32 v31, v31
	v_add_f32_e32 v110, v28, v110
	v_add_f32_e32 v110, v61, v110
	v_add_f32_e32 v110, v99, v110
	v_sub_f32_e32 v108, v38, v108
	v_add_f32_e32 v110, v31, v110
	v_mul_f32_e32 v108, 0x3fb8aa3b, v108
	v_exp_f32_e32 v108, v108
	v_add_f32_dpp v110, v110, v110 quad_perm:[1,0,3,2] row_mask:0xf bank_mask:0xf bound_ctrl:1
	v_cvt_pk_bf16_f32 v8, v8, s0
	ds_write_b16 v79, v12 offset:432
	v_add_f32_dpp v110, v110, v110 quad_perm:[2,3,0,1] row_mask:0xf bank_mask:0xf bound_ctrl:1
	v_mul_f32_e32 v12, v27, v95
	ds_write_b16 v79, v9 offset:560
	v_add_f32_dpp v110, v110, v110 row_half_mirror row_mask:0xf bank_mask:0xf bound_ctrl:1
	v_mul_f32_e32 v9, v109, v95
	ds_write_b16 v79, v8 offset:592
	v_add_f32_dpp v110, v110, v110 row_mirror row_mask:0xf bank_mask:0xf bound_ctrl:1
	v_add_f32_e32 v108, v108, v110
	v_rcp_f32_e32 v108, v108
	v_mul_f32_e32 v8, v59, v95
	v_cvt_pk_bf16_f32 v12, v12, s0
	v_cvt_pk_bf16_f32 v9, v9, s0
	v_mul_f32_e32 v14, v16, v108
	v_mul_f32_e32 v10, v25, v108
	v_cvt_pk_bf16_f32 v14, v14, s0
	v_cvt_pk_bf16_f32 v10, v10, s0
	ds_write_b16 v79, v14 offset:1008
	v_mul_f32_e32 v14, v29, v30
	ds_write_b16 v79, v10 offset:1136
	v_mul_f32_e32 v10, v13, v30
	v_cvt_pk_bf16_f32 v14, v14, s0
	v_cvt_pk_bf16_f32 v10, v10, s0
	ds_write_b16 v79, v14 offset:32
	v_mul_f32_e32 v14, v26, v60
	ds_write_b16 v79, v10 offset:160
	v_mul_f32_e32 v10, v100, v60
	v_cvt_pk_bf16_f32 v14, v14, s0
	v_cvt_pk_bf16_f32 v10, v10, s0
	ds_write_b16 v79, v14 offset:368
	v_mul_f32_e32 v14, v20, v95
	ds_write_b16 v79, v10 offset:496
	v_mul_f32_e32 v10, v98, v95
	v_cvt_pk_bf16_f32 v14, v14, s0
	v_cvt_pk_bf16_f32 v10, v10, s0
	ds_write_b16 v79, v14 offset:704
	v_mul_f32_e32 v14, v17, v108
	ds_write_b16 v79, v10 offset:832
	v_mul_f32_e32 v10, v28, v108
	v_cvt_pk_bf16_f32 v14, v14, s0
	v_cvt_pk_bf16_f32 v10, v10, s0
	ds_write_b16 v79, v14 offset:1040
	v_mul_f32_e32 v14, v15, v30
	ds_write_b16 v79, v10 offset:1168
	v_mul_f32_e32 v10, v11, v30
	v_cvt_pk_bf16_f32 v14, v14, s0
	v_cvt_pk_bf16_f32 v10, v10, s0
	ds_write_b16 v79, v14 offset:64
	v_mul_f32_e32 v14, v56, v60
	ds_write_b16 v79, v10 offset:192
	v_mul_f32_e32 v10, v101, v60
	v_cvt_pk_bf16_f32 v14, v14, s0
	v_cvt_pk_bf16_f32 v10, v10, s0
	ds_write_b16 v79, v14 offset:400
	v_mul_f32_e32 v14, v23, v95
	ds_write_b16 v79, v10 offset:528
	v_mul_f32_e32 v10, v102, v95
	v_cvt_pk_bf16_f32 v14, v14, s0
	v_cvt_pk_bf16_f32 v10, v10, s0
	v_cvt_pk_bf16_f32 v8, v8, s0
	ds_write_b16 v79, v14 offset:736
	v_mul_f32_e32 v14, v19, v108
	ds_write_b16 v79, v12 offset:768
	v_mul_f32_e32 v12, v21, v108
	ds_write_b16 v79, v10 offset:864
	v_mul_f32_e32 v10, v61, v108
	ds_write_b16 v79, v9 offset:896
	v_mul_f32_e32 v9, v99, v108
	ds_write_b16 v79, v8 offset:928
	v_mul_f32_e32 v8, v31, v108
	v_cvt_pk_bf16_f32 v14, v14, s0
	v_cvt_pk_bf16_f32 v12, v12, s0
	v_cvt_pk_bf16_f32 v10, v10, s0
	v_cvt_pk_bf16_f32 v9, v9, s0
	v_cvt_pk_bf16_f32 v8, v8, s0
	ds_write_b16 v79, v14 offset:1072
	ds_write_b16 v79, v12 offset:1104
	ds_write_b16 v79, v10 offset:1200
	ds_write_b16 v79, v9 offset:1232
	ds_write_b16 v79, v8 offset:1264
	ds_write_b16 v79, v39 offset:288
	ds_write_b16 v79, v39 offset:624
	ds_write_b16 v79, v39 offset:960
	ds_write_b16 v79, v39 offset:1296
	s_waitcnt lgkmcnt(0)
	ds_read_b128 v[8:11], v77
	v_add_u32_e32 v25, -8, v94
	v_xor_b32_e32 v12, v25, v78
	v_xor_b32_e32 v16, v25, v82
	v_xor_b32_e32 v20, v25, v83
	v_xor_b32_e32 v25, v25, v84
	v_lshl_add_u32 v12, v12, 4, v80
	v_lshl_add_u32 v16, v16, 4, v80
	v_lshl_add_u32 v20, v20, 4, v80
	v_lshl_add_u32 v25, v25, 4, v81
	ds_read_b128 v[12:15], v12 offset:36864
	ds_read_b128 v[16:19], v16 offset:47872
	ds_read_b128 v[20:23], v20 offset:58880
	ds_read_b128 v[26:29], v25 offset:33024
	v_add_u32_e32 v25, -4, v94
	v_xor_b32_e32 v30, v25, v78
	v_lshl_add_u32 v30, v30, 4, v80
	ds_read_b128 v[56:59], v30 offset:36864
	s_waitcnt lgkmcnt(4)
	v_mfma_f32_16x16x32_bf16 v[12:15], v[8:11], v[12:15], 0
	v_xor_b32_e32 v30, v25, v82
	v_lshl_add_u32 v30, v30, 4, v80
	v_mov_b32_e32 v95, v24
	s_waitcnt lgkmcnt(3)
; __device__ __forceinline__ unsigned f2bf(float f) { return pk2(f, f) & 0xffffu; }
; #define LDS_WAIT() asm volatile("s_waitcnt lgkmcnt(0)" ::: "memory")
; __device__ __forceinline__ void attn_unit(const AtArgs& A, unsigned char* lds, int unit, int tid, int wave, int lane) {
;     ...
; #pragma unroll
;         for (int ks = 0; ks < 5; ++ks) {
;             const bf16x8 pa = *(const bf16x8*)(PS + fr * PST + ks * 32 + fq * 8);
; #pragma unroll
;             for (int dt = 0; dt < 4; ++dt) {
;                 const bf16x8 vb = *(const bf16x8*)(VT + (dt * 16 + fr) * VST + (((((q0 + ks * 32) >> 3) + fq) ^ ((dt * 2 + (fr >> 3)) & 7)) << 3));
;                 o[dt] = __builtin_amdgcn_mfma_f32_16x16x32_bf16(pa, vb, o[dt], 0, 0, 0);
;             }
;         }
;         LDS_WAIT();
; #pragma unroll
;         for (int r = 0; r < 4; ++r)
; #pragma unroll
;             for (int dt = 0; dt < 4; ++dt) PS[(fq * 4 + r) * PST + dt * 16 + fr] = (bf16)f2bf(o[dt][r]);
;         LDS_WAIT();
; #pragma unroll
;         for (int j = 0; j < 2; ++j) {
;             const int tk = (lane >> 3) + 8 * j, c16 = lane & 7;
;             const size_t t = (size_t)b * SEQ + nb * 128 + q0 + tk;
;             *(u32x4*)(YB + t * 512 + hq * 64 + c16 * 8) = *(const u32x4*)(PS + tk * PST + c16 * 8);
;         }
;         LDS_WAIT();
	v_mfma_f32_16x16x32_bf16 v[16:19], v[8:11], v[16:19], 0
	s_waitcnt lgkmcnt(2)
	v_mfma_f32_16x16x32_bf16 v[20:23], v[8:11], v[20:23], 0
	s_waitcnt lgkmcnt(1)
	v_mfma_f32_16x16x32_bf16 v[8:11], v[8:11], v[26:29], 0
	ds_read_b128 v[26:29], v77 offset:64
	s_waitcnt lgkmcnt(0)
	v_mfma_f32_16x16x32_bf16 v[12:15], v[26:29], v[56:59], v[12:15]
	ds_read_b128 v[56:59], v30 offset:47872
	v_xor_b32_e32 v30, v25, v83
	v_lshl_add_u32 v30, v30, 4, v80
	s_waitcnt lgkmcnt(0)
	v_mfma_f32_16x16x32_bf16 v[16:19], v[26:29], v[56:59], v[16:19]
	ds_read_b128 v[56:59], v30 offset:58880
	v_xor_b32_e32 v25, v25, v84
	v_lshl_add_u32 v25, v25, 4, v81
	s_waitcnt lgkmcnt(0)
	v_mfma_f32_16x16x32_bf16 v[20:23], v[26:29], v[56:59], v[20:23]
	ds_read_b128 v[56:59], v25 offset:33024
	v_xor_b32_e32 v25, v94, v78
	v_lshl_add_u32 v25, v25, 4, v80
	s_waitcnt lgkmcnt(0)
	v_mfma_f32_16x16x32_bf16 v[8:11], v[26:29], v[56:59], v[8:11]
	ds_read_b128 v[26:29], v77 offset:128
	ds_read_b128 v[56:59], v25 offset:36864
	v_xor_b32_e32 v25, v94, v82
	v_lshl_add_u32 v25, v25, 4, v80
	s_waitcnt lgkmcnt(0)
	v_mfma_f32_16x16x32_bf16 v[12:15], v[26:29], v[56:59], v[12:15]
	ds_read_b128 v[56:59], v25 offset:47872
	v_xor_b32_e32 v25, v94, v83
	v_lshl_add_u32 v25, v25, 4, v80
	s_waitcnt lgkmcnt(0)
	v_mfma_f32_16x16x32_bf16 v[16:19], v[26:29], v[56:59], v[16:19]
	ds_read_b128 v[56:59], v25 offset:58880
	v_add_u32_e32 v25, 4, v94
	s_waitcnt lgkmcnt(0)
	v_mfma_f32_16x16x32_bf16 v[56:59], v[26:29], v[56:59], v[20:23]
	s_nop 2
	v_xor_b32_e32 v20, v94, v84
	v_lshl_add_u32 v20, v20, 4, v81
	ds_read_b128 v[20:23], v20 offset:33024
	s_waitcnt lgkmcnt(0)
	v_mfma_f32_16x16x32_bf16 v[8:11], v[26:29], v[20:23], v[8:11]
	ds_read_b128 v[26:29], v77 offset:192
	v_xor_b32_e32 v20, v25, v78
	v_lshl_add_u32 v20, v20, 4, v80
	ds_read_b128 v[20:23], v20 offset:36864
	s_waitcnt lgkmcnt(0)
	v_mfma_f32_16x16x32_bf16 v[20:23], v[26:29], v[20:23], v[12:15]
	s_nop 2
	v_xor_b32_e32 v12, v25, v82
	v_lshl_add_u32 v12, v12, 4, v80
	ds_read_b128 v[12:15], v12 offset:47872
	s_waitcnt lgkmcnt(0)
	v_mfma_f32_16x16x32_bf16 v[16:19], v[26:29], v[12:15], v[16:19]
	v_xor_b32_e32 v12, v25, v83
	v_lshl_add_u32 v12, v12, 4, v80
	ds_read_b128 v[12:15], v12 offset:58880
	v_xor_b32_e32 v25, v25, v84
	v_lshl_add_u32 v25, v25, 4, v81
	s_waitcnt lgkmcnt(0)
	v_mfma_f32_16x16x32_bf16 v[12:15], v[26:29], v[12:15], v[56:59]
	s_nop 2
	ds_read_b128 v[56:59], v25 offset:33024
	v_add_u32_e32 v25, 8, v94
	s_waitcnt lgkmcnt(0)
	v_mfma_f32_16x16x32_bf16 v[8:11], v[26:29], v[56:59], v[8:11]
	ds_read_b128 v[26:29], v77 offset:256
	v_xor_b32_e32 v30, v25, v78
	v_lshl_add_u32 v30, v30, 4, v80
	ds_read_b128 v[56:59], v30 offset:36864
	v_xor_b32_e32 v30, v25, v82
	v_lshl_add_u32 v30, v30, 4, v80
	s_waitcnt lgkmcnt(0)
	v_mfma_f32_16x16x32_bf16 v[20:23], v[26:29], v[56:59], v[20:23]
	ds_read_b128 v[56:59], v30 offset:47872
	v_xor_b32_e32 v30, v25, v83
	v_lshl_add_u32 v30, v30, 4, v80
	s_waitcnt lgkmcnt(0)
	v_mfma_f32_16x16x32_bf16 v[16:19], v[26:29], v[56:59], v[16:19]
	ds_read_b128 v[56:59], v30 offset:58880
	v_xor_b32_e32 v25, v25, v84
	v_lshl_add_u32 v25, v25, 4, v81
	s_waitcnt lgkmcnt(0)
	v_mfma_f32_16x16x32_bf16 v[12:15], v[26:29], v[56:59], v[12:15]
	ds_read_b128 v[56:59], v25 offset:33024
	s_waitcnt lgkmcnt(0)
	v_cvt_pk_bf16_f32 v20, v20, s0
	s_waitcnt lgkmcnt(0)
	v_mfma_f32_16x16x32_bf16 v[8:11], v[26:29], v[56:59], v[8:11]
	v_cvt_pk_bf16_f32 v16, v16, s0
	s_nop 2
	v_cvt_pk_bf16_f32 v12, v12, s0
	ds_write_b16 v79, v20
	s_nop 1
	v_cvt_pk_bf16_f32 v8, v8, s0
	ds_write_b16 v79, v8 offset:96
	v_cvt_pk_bf16_f32 v8, v21, s0
	ds_write_b16 v79, v8 offset:336
	v_cvt_pk_bf16_f32 v8, v17, s0
	ds_write_b16 v79, v8 offset:368
	v_cvt_pk_bf16_f32 v8, v13, s0
	ds_write_b16 v79, v8 offset:400
	v_cvt_pk_bf16_f32 v8, v9, s0
	ds_write_b16 v79, v8 offset:432
	v_cvt_pk_bf16_f32 v8, v22, s0
	ds_write_b16 v79, v8 offset:672
	v_cvt_pk_bf16_f32 v8, v18, s0
	ds_write_b16 v79, v8 offset:704
	v_cvt_pk_bf16_f32 v8, v14, s0
	ds_write_b16 v79, v8 offset:736
	v_cvt_pk_bf16_f32 v8, v10, s0
	ds_write_b16 v79, v8 offset:768
	v_cvt_pk_bf16_f32 v8, v23, s0
	ds_write_b16 v79, v8 offset:1008
	v_cvt_pk_bf16_f32 v8, v19, s0
	ds_write_b16 v79, v8 offset:1040
	v_cvt_pk_bf16_f32 v8, v15, s0
	ds_write_b16 v79, v8 offset:1072
	v_cvt_pk_bf16_f32 v8, v11, s0
	ds_write_b16 v79, v16 offset:32
	ds_write_b16 v79, v12 offset:64
	ds_write_b16 v79, v8 offset:1104
	s_waitcnt lgkmcnt(0)
	ds_read_b128 v[8:11], v92
	v_lshl_add_u64 v[12:13], v[52:53], 0, s[20:21]
	s_mov_b32 s0, 0x1d800000
	v_add_co_u32_e32 v14, vcc, s0, v12
	s_mov_b32 s0, 0x1d802000
	s_nop 0
	v_addc_co_u32_e32 v15, vcc, 0, v13, vcc
	s_waitcnt lgkmcnt(0)
	global_store_dwordx4 v[14:15], v[8:11], off
	ds_read_b128 v[8:11], v92 offset:2688
	v_add_co_u32_e32 v12, vcc, s0, v12
	s_add_u32 s20, s20, 0x4000
	s_nop 0
	v_addc_co_u32_e32 v13, vcc, 0, v13, vcc
	s_waitcnt lgkmcnt(0)
	global_store_dwordx4 v[12:13], v[8:11], off
	s_waitcnt lgkmcnt(0)
	s_addc_u32 s21, s21, 0
	s_mov_b64 s[0:1], 0x400
	v_mov_b64_e32 v[14:15], v[6:7]
	v_mov_b64_e32 v[10:11], v[2:3]
	v_add_u32_e32 v94, 2, v94
	v_lshl_add_u64 v[54:55], v[54:55], 0, s[0:1]
	s_cmp_lg_u32 s2, 64
	v_mov_b64_e32 v[12:13], v[4:5]
	v_mov_b64_e32 v[8:9], v[0:1]
	s_cbranch_scc0 .LBB0_492
